# SWA in-proj GEMM epilogue: rope table staged in LDS once per phase, 16 serialized load->vmcnt(0) round trips per unit removed, straight-line rope math
# speedup vs baseline: 1.0100x; 1.0078x over previous
.LBB0_931:
	v_mov_b32_e32 v129, 0
	ds_read_b64 v[0:1], v129 offset:216
	s_cmpk_gt_i32 s33, 0x527
	v_readfirstlane_b32 s2, v154
	s_waitcnt lgkmcnt(0)
	v_readfirstlane_b32 s3, v1
	v_readfirstlane_b32 s10, v0
	s_cbranch_scc1 .LBB0_979
	v_lshlrev_b32_e32 v0, 5, v154
	s_add_u32 s98, s10, 0x20fc000
	s_addc_u32 s99, s3, 0
	global_load_dwordx4 v[2:5], v0, s[98:99]
	global_load_dwordx4 v[6:9], v0, s[98:99] offset:16
	v_lshrrev_b32_e32 v1, 2, v154
	v_and_b32_e32 v0, 3, v154
	v_mul_u32_u24_e32 v1, 0x90, v1
	v_lshl_add_u32 v0, v0, 5, v1
	v_add_u32_e32 v0, 0x20100, v0
	s_waitcnt vmcnt(0)
	ds_write_b128 v0, v[2:5]
	ds_write_b128 v0, v[6:9] offset:16
	s_waitcnt lgkmcnt(0)
	v_lshlrev_b32_e32 v0, 4, v154
	s_add_u32 s36, s10, 0x2920000
	v_and_b32_e32 v1, 32, v154
	v_bfe_u32 v10, v154, 2, 4
	v_lshrrev_b32_e32 v2, 3, v154
	s_movk_i32 s0, 0x70
	v_add_u32_e32 v11, 0x2000, v0
	s_addc_u32 s37, s3, 0
	v_bitop3_b32 v8, v0, v1, 48 bitop3:0x6c
	v_and_or_b32 v2, v2, s0, v10
	v_lshrrev_b32_e32 v0, 7, v11
	s_movk_i32 s0, 0xf0
	s_add_u32 s38, s10, 0x1100000
	v_and_or_b32 v0, v0, s0, v10
	s_mul_hi_i32 s0, s33, 0x66666667
	s_addc_u32 s39, s3, 0
	s_lshr_b32 s1, s0, 31
	s_ashr_i32 s0, s0, 4
	s_add_i32 s0, s0, s1
	s_mul_i32 s1, s0, 40
	s_sub_i32 s1, s33, s1
	s_lshl_b32 s0, s0, 2
	s_and_b32 s4, s1, 3
	s_or_b32 s26, s4, s0
	s_ashr_i32 s24, s1, 2
	s_lshr_b32 s13, s2, 6
	s_ashr_i32 s27, s26, 31
	s_ashr_i32 s25, s24, 31
	s_lshr_b32 s12, s2, 8
	s_lshl_b32 s40, s13, 10
	s_lshl_b64 s[0:1], s[26:27], 19
	s_lshl_b64 s[4:5], s[24:25], 19
	v_and_b32_e32 v9, 64, v154
	s_add_u32 s30, s38, s4
	v_or_b32_e32 v1, v8, v9
	s_addc_u32 s31, s39, s5
	s_add_i32 s41, s40, 0xf0
	v_lshl_or_b32 v128, v2, 11, v1
	s_add_i32 m0, s41, 0x10000
	v_lshl_or_b32 v130, v0, 11, v1
	global_load_lds_dwordx4 v128, s[30:31]
	s_add_i32 m0, s41, 0x12000
	s_add_u32 s4, s30, 0x40000
	global_load_lds_dwordx4 v130, s[30:31]
	s_addc_u32 s5, s31, 0
	s_add_i32 m0, s41, 0x14000
	v_mov_b32_e32 v131, v129
	global_load_lds_dwordx4 v128, s[4:5]
	s_add_i32 m0, s41, 0x16000
	s_add_u32 s28, s36, s0
	s_addc_u32 s29, s37, s1
	s_add_i32 s42, s41, 0x2000
	global_load_lds_dwordx4 v130, s[4:5]
	s_mov_b32 m0, s41
	s_add_u32 s0, s28, 0x40000
	global_load_lds_dwordx4 v128, s[28:29]
	s_mov_b32 m0, s42
	s_addc_u32 s1, s29, 0
	s_add_i32 s43, s41, 0x4000
	global_load_lds_dwordx4 v130, s[28:29]
	s_mov_b32 m0, s43
	s_add_i32 s44, s41, 0x6000
	global_load_lds_dwordx4 v128, s[0:1]
	s_mov_b32 m0, s44
	s_cmp_eq_u32 s12, 1
	global_load_lds_dwordx4 v130, s[0:1]
	s_mov_b32 s4, 0x10000
	v_lshl_add_u64 v[6:7], s[30:31], 0, v[128:129]
	v_lshl_add_u64 v[4:5], s[30:31], 0, v[130:131]
	s_mov_b32 s5, 0x14000
	v_lshl_add_u64 v[2:3], s[28:29], 0, v[128:129]
	s_cselect_b64 s[0:1], -1, 0
	s_cmp_lg_u32 s12, 1
	v_lshl_add_u64 v[0:1], s[28:29], 0, v[130:131]
	s_cbranch_scc1 .LBB0_934
	s_barrier

.LBB0_943:
	s_lshl_b32 s17, s26, 8
	s_add_i32 s17, s17, s47
	s_lshl_b32 s19, s24, 8
	s_or_b32 s24, s19, s48
	s_ashr_i32 s25, s24, 31
	v_or_b32_e32 v153, s17, v142
	v_mov_b64_e32 v[156:157], s[8:9]
	s_mov_b32 s98, 0x14000
	s_mov_b32 s99, 0
	v_mad_i64_i32 v[156:157], s[28:29], v153, s56, v[156:157]
	s_mov_b32 s100, 0x64000
	s_mov_b32 s101, 0
	v_lshl_add_u64 v[156:157], s[24:25], 1, v[156:157]
	v_lshl_add_u64 v[156:157], v[156:157], 0, v[132:133]
	s_cmpk_ge_i32 s24, 0x500
	s_cbranch_scc1 .Lrope_plain
	s_cmp_ge_i32 s17, s52
	s_cbranch_scc1 .Lrope_plain
	s_bfe_u32 s19, s17, 0x70006
	s_add_i32 s27, s17, 0x80
	s_mul_i32 s19, s19, 0x90
	s_bfe_u32 s27, s27, 0x70006
	s_add_i32 s19, s19, 0x20100
	s_mul_i32 s27, s27, 0x90
	v_mul_u32_u24_e32 v153, 0x90, v142
	s_add_i32 s27, s27, 0x20100
	v_lshl_add_u32 v153, v143, 2, v153
	v_lshl_add_u32 v158, v143, 2, s19
	v_add_u32_e32 v153, 0x20100, v153
	v_lshl_add_u32 v159, v143, 2, s27
	v_cndmask_b32_e64 v152, v153, v158, s[2:3]
	ds_read_b128 v[160:163], v152
	ds_read_b128 v[164:167], v152 offset:16
	v_add_u32_e32 v152, 0x900, v153
	v_cndmask_b32_e64 v152, v152, v158, s[2:3]
	ds_read_b128 v[168:171], v152
	ds_read_b128 v[172:175], v152 offset:16
	v_add_u32_e32 v152, 0x1200, v153
	v_cndmask_b32_e64 v152, v152, v158, s[2:3]
	ds_read_b128 v[176:179], v152
	ds_read_b128 v[180:183], v152 offset:16
	v_add_u32_e32 v152, 0x1b00, v153
	v_cndmask_b32_e64 v152, v152, v158, s[2:3]
	ds_read_b128 v[184:187], v152
	ds_read_b128 v[188:191], v152 offset:16
	v_cndmask_b32_e64 v152, v153, v159, s[2:3]
	ds_read_b128 v[192:195], v152
	ds_read_b128 v[196:199], v152 offset:16
	v_add_u32_e32 v152, 0x900, v153
	v_cndmask_b32_e64 v152, v152, v159, s[2:3]
	ds_read_b128 v[200:203], v152
	ds_read_b128 v[204:207], v152 offset:16
	v_add_u32_e32 v152, 0x1200, v153
	v_cndmask_b32_e64 v152, v152, v159, s[2:3]
	ds_read_b128 v[208:211], v152
	ds_read_b128 v[212:215], v152 offset:16
	v_add_u32_e32 v152, 0x1b00, v153
	v_cndmask_b32_e64 v152, v152, v159, s[2:3]
	ds_read_b128 v[216:219], v152
	ds_read_b128 v[220:223], v152 offset:16
	s_waitcnt lgkmcnt(14)
	v_mul_f32_e32 v224, v120, v161
	v_mul_f32_e32 v225, v121, v163
	v_mul_f32_e32 v226, v124, v161
	v_mul_f32_e32 v227, v125, v163
	v_mul_f32_e32 v228, v126, v164
	v_mul_f32_e32 v229, v122, v165
	v_mul_f32_e32 v230, v122, v164
	v_mul_f32_e32 v231, v126, v165
	v_fma_f32 v124, v124, v160, -v224
	v_fma_f32 v125, v125, v162, -v225
	v_fma_f32 v120, v120, v160, v226
	v_fma_f32 v121, v121, v162, v227
	v_sub_f32_e32 v126, v228, v229
	v_add_f32_e32 v122, v230, v231
	v_mul_f32_e32 v224, v127, v166
	v_mul_f32_e32 v225, v123, v167
	v_mul_f32_e32 v226, v123, v166
	v_mul_f32_e32 v227, v127, v167
	v_sub_f32_e32 v127, v224, v225
	v_add_f32_e32 v123, v226, v227
	v_cvt_pk_bf16_f32 v124, v124, v125
	v_cvt_pk_bf16_f32 v125, v126, v127
	v_cvt_pk_bf16_f32 v126, v120, v121
	v_cvt_pk_bf16_f32 v127, v122, v123
	global_store_dwordx2 v[156:157], v[124:125], off
	global_store_dwordx2 v[156:157], v[126:127], off offset:32
	v_mul_f32_e32 v224, v112, v161
	v_mul_f32_e32 v225, v113, v163
	v_mul_f32_e32 v226, v116, v161
	v_mul_f32_e32 v227, v117, v163
	v_mul_f32_e32 v228, v118, v164
	v_mul_f32_e32 v229, v114, v165
	v_mul_f32_e32 v230, v114, v164
	v_mul_f32_e32 v231, v118, v165
	v_fma_f32 v116, v116, v160, -v224
	v_fma_f32 v117, v117, v162, -v225
	v_fma_f32 v112, v112, v160, v226
	v_fma_f32 v113, v113, v162, v227
	v_sub_f32_e32 v118, v228, v229
	v_add_f32_e32 v114, v230, v231
	v_mul_f32_e32 v224, v119, v166
	v_mul_f32_e32 v225, v115, v167
	v_mul_f32_e32 v226, v115, v166
	v_mul_f32_e32 v227, v119, v167
	v_sub_f32_e32 v119, v224, v225
	v_add_f32_e32 v115, v226, v227
	v_cvt_pk_bf16_f32 v116, v116, v117
	v_cvt_pk_bf16_f32 v117, v118, v119
	v_cvt_pk_bf16_f32 v118, v112, v113
	v_cvt_pk_bf16_f32 v119, v114, v115
	global_store_dwordx2 v[156:157], v[116:117], off offset:256
	global_store_dwordx2 v[156:157], v[118:119], off offset:288
	v_lshl_add_u64 v[156:157], v[156:157], 0, s[98:99]
	s_waitcnt lgkmcnt(12)
	v_mul_f32_e32 v224, v104, v169
	v_mul_f32_e32 v225, v105, v171
	v_mul_f32_e32 v226, v108, v169
	v_mul_f32_e32 v227, v109, v171
	v_mul_f32_e32 v228, v110, v172
	v_mul_f32_e32 v229, v106, v173
	v_mul_f32_e32 v230, v106, v172
	v_mul_f32_e32 v231, v110, v173
	v_fma_f32 v108, v108, v168, -v224
	v_fma_f32 v109, v109, v170, -v225
	v_fma_f32 v104, v104, v168, v226
	v_fma_f32 v105, v105, v170, v227
	v_sub_f32_e32 v110, v228, v229
	v_add_f32_e32 v106, v230, v231
	v_mul_f32_e32 v224, v111, v174
	v_mul_f32_e32 v225, v107, v175
	v_mul_f32_e32 v226, v107, v174
	v_mul_f32_e32 v227, v111, v175
	v_sub_f32_e32 v111, v224, v225
	v_add_f32_e32 v107, v226, v227
	v_cvt_pk_bf16_f32 v108, v108, v109
	v_cvt_pk_bf16_f32 v109, v110, v111
	v_cvt_pk_bf16_f32 v110, v104, v105
	v_cvt_pk_bf16_f32 v111, v106, v107
	global_store_dwordx2 v[156:157], v[108:109], off
	global_store_dwordx2 v[156:157], v[110:111], off offset:32
	v_mul_f32_e32 v224, v96, v169
	v_mul_f32_e32 v225, v97, v171
	v_mul_f32_e32 v226, v100, v169
	v_mul_f32_e32 v227, v101, v171
	v_mul_f32_e32 v228, v102, v172
	v_mul_f32_e32 v229, v98, v173
	v_mul_f32_e32 v230, v98, v172
	v_mul_f32_e32 v231, v102, v173
	v_fma_f32 v100, v100, v168, -v224
	v_fma_f32 v101, v101, v170, -v225
	v_fma_f32 v96, v96, v168, v226
	v_fma_f32 v97, v97, v170, v227
	v_sub_f32_e32 v102, v228, v229
	v_add_f32_e32 v98, v230, v231
	v_mul_f32_e32 v224, v103, v174
	v_mul_f32_e32 v225, v99, v175
	v_mul_f32_e32 v226, v99, v174
	v_mul_f32_e32 v227, v103, v175
	v_sub_f32_e32 v103, v224, v225
	v_add_f32_e32 v99, v226, v227
	v_cvt_pk_bf16_f32 v100, v100, v101
	v_cvt_pk_bf16_f32 v101, v102, v103
	v_cvt_pk_bf16_f32 v102, v96, v97
	v_cvt_pk_bf16_f32 v103, v98, v99
	global_store_dwordx2 v[156:157], v[100:101], off offset:256
	global_store_dwordx2 v[156:157], v[102:103], off offset:288
	v_lshl_add_u64 v[156:157], v[156:157], 0, s[98:99]
	s_waitcnt lgkmcnt(10)
	v_mul_f32_e32 v224, v88, v177
	v_mul_f32_e32 v225, v89, v179
	v_mul_f32_e32 v226, v92, v177
	v_mul_f32_e32 v227, v93, v179
	v_mul_f32_e32 v228, v94, v180
	v_mul_f32_e32 v229, v90, v181
	v_mul_f32_e32 v230, v90, v180
	v_mul_f32_e32 v231, v94, v181
	v_fma_f32 v92, v92, v176, -v224
	v_fma_f32 v93, v93, v178, -v225
	v_fma_f32 v88, v88, v176, v226
	v_fma_f32 v89, v89, v178, v227
	v_sub_f32_e32 v94, v228, v229
	v_add_f32_e32 v90, v230, v231
	v_mul_f32_e32 v224, v95, v182
	v_mul_f32_e32 v225, v91, v183
	v_mul_f32_e32 v226, v91, v182
	v_mul_f32_e32 v227, v95, v183
	v_sub_f32_e32 v95, v224, v225
	v_add_f32_e32 v91, v226, v227
	v_cvt_pk_bf16_f32 v92, v92, v93
	v_cvt_pk_bf16_f32 v93, v94, v95
	v_cvt_pk_bf16_f32 v94, v88, v89
	v_cvt_pk_bf16_f32 v95, v90, v91
	global_store_dwordx2 v[156:157], v[92:93], off
	global_store_dwordx2 v[156:157], v[94:95], off offset:32
	v_mul_f32_e32 v224, v80, v177
	v_mul_f32_e32 v225, v81, v179
	v_mul_f32_e32 v226, v84, v177
	v_mul_f32_e32 v227, v85, v179
	v_mul_f32_e32 v228, v86, v180
	v_mul_f32_e32 v229, v82, v181
	v_mul_f32_e32 v230, v82, v180
	v_mul_f32_e32 v231, v86, v181
	v_fma_f32 v84, v84, v176, -v224
	v_fma_f32 v85, v85, v178, -v225
	v_fma_f32 v80, v80, v176, v226
	v_fma_f32 v81, v81, v178, v227
	v_sub_f32_e32 v86, v228, v229
	v_add_f32_e32 v82, v230, v231
	v_mul_f32_e32 v224, v87, v182
	v_mul_f32_e32 v225, v83, v183
	v_mul_f32_e32 v226, v83, v182
	v_mul_f32_e32 v227, v87, v183
	v_sub_f32_e32 v87, v224, v225
	v_add_f32_e32 v83, v226, v227
	v_cvt_pk_bf16_f32 v84, v84, v85
	v_cvt_pk_bf16_f32 v85, v86, v87
	v_cvt_pk_bf16_f32 v86, v80, v81
	v_cvt_pk_bf16_f32 v87, v82, v83
	global_store_dwordx2 v[156:157], v[84:85], off offset:256
	global_store_dwordx2 v[156:157], v[86:87], off offset:288
	v_lshl_add_u64 v[156:157], v[156:157], 0, s[98:99]
	s_waitcnt lgkmcnt(8)
	v_mul_f32_e32 v224, v72, v185
	v_mul_f32_e32 v225, v73, v187
	v_mul_f32_e32 v226, v76, v185
	v_mul_f32_e32 v227, v77, v187
	v_mul_f32_e32 v228, v78, v188
	v_mul_f32_e32 v229, v74, v189
	v_mul_f32_e32 v230, v74, v188
	v_mul_f32_e32 v231, v78, v189
	v_fma_f32 v76, v76, v184, -v224
	v_fma_f32 v77, v77, v186, -v225
	v_fma_f32 v72, v72, v184, v226
	v_fma_f32 v73, v73, v186, v227
	v_sub_f32_e32 v78, v228, v229
	v_add_f32_e32 v74, v230, v231
	v_mul_f32_e32 v224, v79, v190
	v_mul_f32_e32 v225, v75, v191
	v_mul_f32_e32 v226, v75, v190
	v_mul_f32_e32 v227, v79, v191
	v_sub_f32_e32 v79, v224, v225
	v_add_f32_e32 v75, v226, v227
	v_cvt_pk_bf16_f32 v76, v76, v77
	v_cvt_pk_bf16_f32 v77, v78, v79
	v_cvt_pk_bf16_f32 v78, v72, v73
	v_cvt_pk_bf16_f32 v79, v74, v75
	global_store_dwordx2 v[156:157], v[76:77], off
	global_store_dwordx2 v[156:157], v[78:79], off offset:32
	v_mul_f32_e32 v224, v64, v185
	v_mul_f32_e32 v225, v65, v187
	v_mul_f32_e32 v226, v68, v185
	v_mul_f32_e32 v227, v69, v187
	v_mul_f32_e32 v228, v70, v188
	v_mul_f32_e32 v229, v66, v189
	v_mul_f32_e32 v230, v66, v188
	v_mul_f32_e32 v231, v70, v189
	v_fma_f32 v68, v68, v184, -v224
	v_fma_f32 v69, v69, v186, -v225
	v_fma_f32 v64, v64, v184, v226
	v_fma_f32 v65, v65, v186, v227
	v_sub_f32_e32 v70, v228, v229
	v_add_f32_e32 v66, v230, v231
	v_mul_f32_e32 v224, v71, v190
	v_mul_f32_e32 v225, v67, v191
	v_mul_f32_e32 v226, v67, v190
	v_mul_f32_e32 v227, v71, v191
	v_sub_f32_e32 v71, v224, v225
	v_add_f32_e32 v67, v226, v227
	v_cvt_pk_bf16_f32 v68, v68, v69
	v_cvt_pk_bf16_f32 v69, v70, v71
	v_cvt_pk_bf16_f32 v70, v64, v65
	v_cvt_pk_bf16_f32 v71, v66, v67
	global_store_dwordx2 v[156:157], v[68:69], off offset:256
	global_store_dwordx2 v[156:157], v[70:71], off offset:288
	v_lshl_add_u64 v[156:157], v[156:157], 0, s[100:101]
	s_waitcnt lgkmcnt(6)
	v_mul_f32_e32 v224, v56, v193
	v_mul_f32_e32 v225, v57, v195
	v_mul_f32_e32 v226, v60, v193
	v_mul_f32_e32 v227, v61, v195
	v_mul_f32_e32 v228, v62, v196
	v_mul_f32_e32 v229, v58, v197
	v_mul_f32_e32 v230, v58, v196
	v_mul_f32_e32 v231, v62, v197
	v_fma_f32 v60, v60, v192, -v224
	v_fma_f32 v61, v61, v194, -v225
	v_fma_f32 v56, v56, v192, v226
	v_fma_f32 v57, v57, v194, v227
	v_sub_f32_e32 v62, v228, v229
	v_add_f32_e32 v58, v230, v231
	v_mul_f32_e32 v224, v63, v198
	v_mul_f32_e32 v225, v59, v199
	v_mul_f32_e32 v226, v59, v198
	v_mul_f32_e32 v227, v63, v199
	v_sub_f32_e32 v63, v224, v225
	v_add_f32_e32 v59, v226, v227
	v_cvt_pk_bf16_f32 v60, v60, v61
	v_cvt_pk_bf16_f32 v61, v62, v63
	v_cvt_pk_bf16_f32 v62, v56, v57
	v_cvt_pk_bf16_f32 v63, v58, v59
	global_store_dwordx2 v[156:157], v[60:61], off
	global_store_dwordx2 v[156:157], v[62:63], off offset:32
	v_mul_f32_e32 v224, v48, v193
	v_mul_f32_e32 v225, v49, v195
	v_mul_f32_e32 v226, v52, v193
	v_mul_f32_e32 v227, v53, v195
	v_mul_f32_e32 v228, v54, v196
	v_mul_f32_e32 v229, v50, v197
	v_mul_f32_e32 v230, v50, v196
	v_mul_f32_e32 v231, v54, v197
	v_fma_f32 v52, v52, v192, -v224
	v_fma_f32 v53, v53, v194, -v225
	v_fma_f32 v48, v48, v192, v226
	v_fma_f32 v49, v49, v194, v227
	v_sub_f32_e32 v54, v228, v229
	v_add_f32_e32 v50, v230, v231
	v_mul_f32_e32 v224, v55, v198
	v_mul_f32_e32 v225, v51, v199
	v_mul_f32_e32 v226, v51, v198
	v_mul_f32_e32 v227, v55, v199
	v_sub_f32_e32 v55, v224, v225
	v_add_f32_e32 v51, v226, v227
	v_cvt_pk_bf16_f32 v52, v52, v53
	v_cvt_pk_bf16_f32 v53, v54, v55
	v_cvt_pk_bf16_f32 v54, v48, v49
	v_cvt_pk_bf16_f32 v55, v50, v51
	global_store_dwordx2 v[156:157], v[52:53], off offset:256
	global_store_dwordx2 v[156:157], v[54:55], off offset:288
	v_lshl_add_u64 v[156:157], v[156:157], 0, s[98:99]
	s_waitcnt lgkmcnt(4)
	v_mul_f32_e32 v224, v40, v201
	v_mul_f32_e32 v225, v41, v203
	v_mul_f32_e32 v226, v44, v201
	v_mul_f32_e32 v227, v45, v203
	v_mul_f32_e32 v228, v46, v204
	v_mul_f32_e32 v229, v42, v205
	v_mul_f32_e32 v230, v42, v204
	v_mul_f32_e32 v231, v46, v205
	v_fma_f32 v44, v44, v200, -v224
	v_fma_f32 v45, v45, v202, -v225
	v_fma_f32 v40, v40, v200, v226
	v_fma_f32 v41, v41, v202, v227
	v_sub_f32_e32 v46, v228, v229
	v_add_f32_e32 v42, v230, v231
	v_mul_f32_e32 v224, v47, v206
	v_mul_f32_e32 v225, v43, v207
	v_mul_f32_e32 v226, v43, v206
	v_mul_f32_e32 v227, v47, v207
	v_sub_f32_e32 v47, v224, v225
	v_add_f32_e32 v43, v226, v227
	v_cvt_pk_bf16_f32 v44, v44, v45
	v_cvt_pk_bf16_f32 v45, v46, v47
	v_cvt_pk_bf16_f32 v46, v40, v41
	v_cvt_pk_bf16_f32 v47, v42, v43
	global_store_dwordx2 v[156:157], v[44:45], off
	global_store_dwordx2 v[156:157], v[46:47], off offset:32
	v_mul_f32_e32 v224, v32, v201
	v_mul_f32_e32 v225, v33, v203
	v_mul_f32_e32 v226, v36, v201
	v_mul_f32_e32 v227, v37, v203
	v_mul_f32_e32 v228, v38, v204
	v_mul_f32_e32 v229, v34, v205
	v_mul_f32_e32 v230, v34, v204
	v_mul_f32_e32 v231, v38, v205
	v_fma_f32 v36, v36, v200, -v224
	v_fma_f32 v37, v37, v202, -v225
	v_fma_f32 v32, v32, v200, v226
	v_fma_f32 v33, v33, v202, v227
	v_sub_f32_e32 v38, v228, v229
	v_add_f32_e32 v34, v230, v231
	v_mul_f32_e32 v224, v39, v206
	v_mul_f32_e32 v225, v35, v207
	v_mul_f32_e32 v226, v35, v206
	v_mul_f32_e32 v227, v39, v207
	v_sub_f32_e32 v39, v224, v225
	v_add_f32_e32 v35, v226, v227
	v_cvt_pk_bf16_f32 v36, v36, v37
	v_cvt_pk_bf16_f32 v37, v38, v39
	v_cvt_pk_bf16_f32 v38, v32, v33
	v_cvt_pk_bf16_f32 v39, v34, v35
	global_store_dwordx2 v[156:157], v[36:37], off offset:256
	global_store_dwordx2 v[156:157], v[38:39], off offset:288
	v_lshl_add_u64 v[156:157], v[156:157], 0, s[98:99]
	s_waitcnt lgkmcnt(2)
	v_mul_f32_e32 v224, v24, v209
	v_mul_f32_e32 v225, v25, v211
	v_mul_f32_e32 v226, v28, v209
	v_mul_f32_e32 v227, v29, v211
	v_mul_f32_e32 v228, v30, v212
	v_mul_f32_e32 v229, v26, v213
	v_mul_f32_e32 v230, v26, v212
	v_mul_f32_e32 v231, v30, v213
	v_fma_f32 v28, v28, v208, -v224
	v_fma_f32 v29, v29, v210, -v225
	v_fma_f32 v24, v24, v208, v226
	v_fma_f32 v25, v25, v210, v227
	v_sub_f32_e32 v30, v228, v229
	v_add_f32_e32 v26, v230, v231
	v_mul_f32_e32 v224, v31, v214
	v_mul_f32_e32 v225, v27, v215
	v_mul_f32_e32 v226, v27, v214
	v_mul_f32_e32 v227, v31, v215
	v_sub_f32_e32 v31, v224, v225
	v_add_f32_e32 v27, v226, v227
	v_cvt_pk_bf16_f32 v28, v28, v29
	v_cvt_pk_bf16_f32 v29, v30, v31
	v_cvt_pk_bf16_f32 v30, v24, v25
	v_cvt_pk_bf16_f32 v31, v26, v27
	global_store_dwordx2 v[156:157], v[28:29], off
	global_store_dwordx2 v[156:157], v[30:31], off offset:32
	v_mul_f32_e32 v224, v16, v209
	v_mul_f32_e32 v225, v17, v211
	v_mul_f32_e32 v226, v20, v209
	v_mul_f32_e32 v227, v21, v211
	v_mul_f32_e32 v228, v22, v212
	v_mul_f32_e32 v229, v18, v213
	v_mul_f32_e32 v230, v18, v212
	v_mul_f32_e32 v231, v22, v213
	v_fma_f32 v20, v20, v208, -v224
	v_fma_f32 v21, v21, v210, -v225
	v_fma_f32 v16, v16, v208, v226
	v_fma_f32 v17, v17, v210, v227
	v_sub_f32_e32 v22, v228, v229
	v_add_f32_e32 v18, v230, v231
	v_mul_f32_e32 v224, v23, v214
	v_mul_f32_e32 v225, v19, v215
	v_mul_f32_e32 v226, v19, v214
	v_mul_f32_e32 v227, v23, v215
	v_sub_f32_e32 v23, v224, v225
	v_add_f32_e32 v19, v226, v227
	v_cvt_pk_bf16_f32 v20, v20, v21
	v_cvt_pk_bf16_f32 v21, v22, v23
	v_cvt_pk_bf16_f32 v22, v16, v17
	v_cvt_pk_bf16_f32 v23, v18, v19
	global_store_dwordx2 v[156:157], v[20:21], off offset:256
	global_store_dwordx2 v[156:157], v[22:23], off offset:288
	v_lshl_add_u64 v[156:157], v[156:157], 0, s[98:99]
	s_waitcnt lgkmcnt(0)
	v_mul_f32_e32 v224, v8, v217
	v_mul_f32_e32 v225, v9, v219
	v_mul_f32_e32 v226, v12, v217
	v_mul_f32_e32 v227, v13, v219
	v_mul_f32_e32 v228, v14, v220
	v_mul_f32_e32 v229, v10, v221
	v_mul_f32_e32 v230, v10, v220
	v_mul_f32_e32 v231, v14, v221
	v_fma_f32 v12, v12, v216, -v224
	v_fma_f32 v13, v13, v218, -v225
	v_fma_f32 v8, v8, v216, v226
	v_fma_f32 v9, v9, v218, v227
	v_sub_f32_e32 v14, v228, v229
	v_add_f32_e32 v10, v230, v231
	v_mul_f32_e32 v224, v15, v222
	v_mul_f32_e32 v225, v11, v223
	v_mul_f32_e32 v226, v11, v222
	v_mul_f32_e32 v227, v15, v223
	v_sub_f32_e32 v15, v224, v225
	v_add_f32_e32 v11, v226, v227
	v_cvt_pk_bf16_f32 v12, v12, v13
	v_cvt_pk_bf16_f32 v13, v14, v15
	v_cvt_pk_bf16_f32 v14, v8, v9
	v_cvt_pk_bf16_f32 v15, v10, v11
	global_store_dwordx2 v[156:157], v[12:13], off
	global_store_dwordx2 v[156:157], v[14:15], off offset:32
	v_mul_f32_e32 v224, v0, v217
	v_mul_f32_e32 v225, v1, v219
	v_mul_f32_e32 v226, v4, v217
	v_mul_f32_e32 v227, v5, v219
	v_mul_f32_e32 v228, v6, v220
	v_mul_f32_e32 v229, v2, v221
	v_mul_f32_e32 v230, v2, v220
	v_mul_f32_e32 v231, v6, v221
	v_fma_f32 v4, v4, v216, -v224
	v_fma_f32 v5, v5, v218, -v225
	v_fma_f32 v0, v0, v216, v226
	v_fma_f32 v1, v1, v218, v227
	v_sub_f32_e32 v6, v228, v229
	v_add_f32_e32 v2, v230, v231
	v_mul_f32_e32 v224, v7, v222
	v_mul_f32_e32 v225, v3, v223
	v_mul_f32_e32 v226, v3, v222
	v_mul_f32_e32 v227, v7, v223
	v_sub_f32_e32 v7, v224, v225
	v_add_f32_e32 v3, v226, v227
	v_cvt_pk_bf16_f32 v4, v4, v5
	v_cvt_pk_bf16_f32 v5, v6, v7
	v_cvt_pk_bf16_f32 v6, v0, v1
	v_cvt_pk_bf16_f32 v7, v2, v3
	global_store_dwordx2 v[156:157], v[4:5], off offset:256
	global_store_dwordx2 v[156:157], v[6:7], off offset:288
	s_branch .Lrope_done
.Lrope_plain:
	v_cvt_pk_bf16_f32 v124, v124, v125
	v_cvt_pk_bf16_f32 v125, v126, v127
	v_cvt_pk_bf16_f32 v126, v120, v121
	v_cvt_pk_bf16_f32 v127, v122, v123
	global_store_dwordx2 v[156:157], v[124:125], off
	global_store_dwordx2 v[156:157], v[126:127], off offset:32
	v_cvt_pk_bf16_f32 v116, v116, v117
	v_cvt_pk_bf16_f32 v117, v118, v119
	v_cvt_pk_bf16_f32 v118, v112, v113
	v_cvt_pk_bf16_f32 v119, v114, v115
	global_store_dwordx2 v[156:157], v[116:117], off offset:256
	global_store_dwordx2 v[156:157], v[118:119], off offset:288
	v_lshl_add_u64 v[156:157], v[156:157], 0, s[98:99]
	v_cvt_pk_bf16_f32 v108, v108, v109
	v_cvt_pk_bf16_f32 v109, v110, v111
	v_cvt_pk_bf16_f32 v110, v104, v105
	v_cvt_pk_bf16_f32 v111, v106, v107
	global_store_dwordx2 v[156:157], v[108:109], off
	global_store_dwordx2 v[156:157], v[110:111], off offset:32
	v_cvt_pk_bf16_f32 v100, v100, v101
	v_cvt_pk_bf16_f32 v101, v102, v103
	v_cvt_pk_bf16_f32 v102, v96, v97
	v_cvt_pk_bf16_f32 v103, v98, v99
	global_store_dwordx2 v[156:157], v[100:101], off offset:256
	global_store_dwordx2 v[156:157], v[102:103], off offset:288
	v_lshl_add_u64 v[156:157], v[156:157], 0, s[98:99]
	v_cvt_pk_bf16_f32 v92, v92, v93
	v_cvt_pk_bf16_f32 v93, v94, v95
	v_cvt_pk_bf16_f32 v94, v88, v89
	v_cvt_pk_bf16_f32 v95, v90, v91
	global_store_dwordx2 v[156:157], v[92:93], off
	global_store_dwordx2 v[156:157], v[94:95], off offset:32
	v_cvt_pk_bf16_f32 v84, v84, v85
	v_cvt_pk_bf16_f32 v85, v86, v87
	v_cvt_pk_bf16_f32 v86, v80, v81
	v_cvt_pk_bf16_f32 v87, v82, v83
	global_store_dwordx2 v[156:157], v[84:85], off offset:256
	global_store_dwordx2 v[156:157], v[86:87], off offset:288
	v_lshl_add_u64 v[156:157], v[156:157], 0, s[98:99]
	v_cvt_pk_bf16_f32 v76, v76, v77
	v_cvt_pk_bf16_f32 v77, v78, v79
	v_cvt_pk_bf16_f32 v78, v72, v73
	v_cvt_pk_bf16_f32 v79, v74, v75
	global_store_dwordx2 v[156:157], v[76:77], off
	global_store_dwordx2 v[156:157], v[78:79], off offset:32
	v_cvt_pk_bf16_f32 v68, v68, v69
	v_cvt_pk_bf16_f32 v69, v70, v71
	v_cvt_pk_bf16_f32 v70, v64, v65
	v_cvt_pk_bf16_f32 v71, v66, v67
	global_store_dwordx2 v[156:157], v[68:69], off offset:256
	global_store_dwordx2 v[156:157], v[70:71], off offset:288
	v_lshl_add_u64 v[156:157], v[156:157], 0, s[100:101]
	v_cvt_pk_bf16_f32 v60, v60, v61
	v_cvt_pk_bf16_f32 v61, v62, v63
	v_cvt_pk_bf16_f32 v62, v56, v57
	v_cvt_pk_bf16_f32 v63, v58, v59
	global_store_dwordx2 v[156:157], v[60:61], off
	global_store_dwordx2 v[156:157], v[62:63], off offset:32
	v_cvt_pk_bf16_f32 v52, v52, v53
	v_cvt_pk_bf16_f32 v53, v54, v55
	v_cvt_pk_bf16_f32 v54, v48, v49
	v_cvt_pk_bf16_f32 v55, v50, v51
	global_store_dwordx2 v[156:157], v[52:53], off offset:256
	global_store_dwordx2 v[156:157], v[54:55], off offset:288
	v_lshl_add_u64 v[156:157], v[156:157], 0, s[98:99]
	v_cvt_pk_bf16_f32 v44, v44, v45
	v_cvt_pk_bf16_f32 v45, v46, v47
	v_cvt_pk_bf16_f32 v46, v40, v41
	v_cvt_pk_bf16_f32 v47, v42, v43
	global_store_dwordx2 v[156:157], v[44:45], off
	global_store_dwordx2 v[156:157], v[46:47], off offset:32
	v_cvt_pk_bf16_f32 v36, v36, v37
	v_cvt_pk_bf16_f32 v37, v38, v39
	v_cvt_pk_bf16_f32 v38, v32, v33
	v_cvt_pk_bf16_f32 v39, v34, v35
	global_store_dwordx2 v[156:157], v[36:37], off offset:256
	global_store_dwordx2 v[156:157], v[38:39], off offset:288
	v_lshl_add_u64 v[156:157], v[156:157], 0, s[98:99]
	v_cvt_pk_bf16_f32 v28, v28, v29
	v_cvt_pk_bf16_f32 v29, v30, v31
	v_cvt_pk_bf16_f32 v30, v24, v25
	v_cvt_pk_bf16_f32 v31, v26, v27
	global_store_dwordx2 v[156:157], v[28:29], off
	global_store_dwordx2 v[156:157], v[30:31], off offset:32
	v_cvt_pk_bf16_f32 v20, v20, v21
	v_cvt_pk_bf16_f32 v21, v22, v23
	v_cvt_pk_bf16_f32 v22, v16, v17
	v_cvt_pk_bf16_f32 v23, v18, v19
	global_store_dwordx2 v[156:157], v[20:21], off offset:256
	global_store_dwordx2 v[156:157], v[22:23], off offset:288
	v_lshl_add_u64 v[156:157], v[156:157], 0, s[98:99]
	v_cvt_pk_bf16_f32 v12, v12, v13
	v_cvt_pk_bf16_f32 v13, v14, v15
	v_cvt_pk_bf16_f32 v14, v8, v9
	v_cvt_pk_bf16_f32 v15, v10, v11
	global_store_dwordx2 v[156:157], v[12:13], off
	global_store_dwordx2 v[156:157], v[14:15], off offset:32
	v_cvt_pk_bf16_f32 v4, v4, v5
	v_cvt_pk_bf16_f32 v5, v6, v7
	v_cvt_pk_bf16_f32 v6, v0, v1
	v_cvt_pk_bf16_f32 v7, v2, v3
	global_store_dwordx2 v[156:157], v[4:5], off offset:256
	global_store_dwordx2 v[156:157], v[6:7], off offset:288
.Lrope_done:
	s_andn2_b64 vcc, exec, s[4:5]
	s_mov_b64 s[4:5], -1
	s_cbranch_vccnz .LBB0_936
	s_andn2_b64 vcc, exec, s[0:1]
	s_cbranch_vccnz .LBB0_935
	s_barrier
	s_branch .LBB0_935
